# grid barriers: no s_sleep in the two hierarchical poll loops
# baseline (speedup 1.0000x reference)
; __device__ __forceinline__ unsigned xb_ld(unsigned* p)              { return __hip_atomic_load(p, __ATOMIC_RELAXED, __HIP_MEMORY_SCOPE_AGENT); }
; __device__ __forceinline__ unsigned xb_add(unsigned* p, unsigned v) { return __hip_atomic_fetch_add(p, v, __ATOMIC_RELAXED, __HIP_MEMORY_SCOPE_AGENT); }
; #define XB_SPIN(cond, bar) do { unsigned _sp = 0; while (cond) { __builtin_amdgcn_s_sleep(1); \
;     if ((++_sp & 255u) == 0u) { if (xb_ld(&(bar)[XB_TMO])) break; if (_sp > XB_SPIN_CAP) { atomicAdd(&(bar)[XB_TMO], 1u); break; } } } } while (0)
; __device__ __forceinline__ void xcd_barrier(const XcdBarrier& b) {
;     ...
;             const unsigned og = xb_add(&bar[XB_TOP], 1u);
;             const unsigned tg = og / nx;
;             if (og + 1u == (tg + 1u) * nx) xb_add(&bar[XB_TOPGEN], 1u);
;             else XB_SPIN(xb_ld(&bar[XB_TOPGEN]) == tg, bar);
.LBB0_768:
	s_and_b32 s20, s24, 0xff
	s_mov_b64 s[18:19], -1
	s_cmp_lg_u32 s20, 0
	s_mov_b64 s[22:23], -1
	s_cbranch_scc0 .LBB0_771
	s_and_b64 vcc, exec, s[22:23]
	s_cbranch_vccz .LBB0_767

; __device__ __forceinline__ unsigned xb_ld(unsigned* p)              { return __hip_atomic_load(p, __ATOMIC_RELAXED, __HIP_MEMORY_SCOPE_AGENT); }
; #define XB_SPIN(cond, bar) do { unsigned _sp = 0; while (cond) { __builtin_amdgcn_s_sleep(1); \
;     if ((++_sp & 255u) == 0u) { if (xb_ld(&(bar)[XB_TMO])) break; if (_sp > XB_SPIN_CAP) { atomicAdd(&(bar)[XB_TMO], 1u); break; } } } } while (0)
; __device__ __forceinline__ void xcd_barrier(const XcdBarrier& b) {
;     ...
;         } else {
;             XB_SPIN(xb_ld(&bar[XB_XGEN(b.x)]) == gen, bar);
.LBB0_785:
	s_and_b32 s18, s22, 0xff
	s_mov_b64 s[16:17], -1
	s_cmp_lg_u32 s18, 0
	s_mov_b64 s[20:21], -1
	s_cbranch_scc0 .LBB0_788
	s_and_b64 vcc, exec, s[20:21]
	s_cbranch_vccz .LBB0_784
